# attention: rebase trigger from the tile row-sum instead of an explicit row max (removes 21 VALU per tile)
# speedup vs baseline: 1.0033x; 1.0023x over previous
.LBB0_130:
	s_or_b64 exec, exec, s[20:21]
	v_add_u32_e32 v4, 0, v4
	v_cmp_lt_i32_e32 vcc, v231, v230
	s_waitcnt vmcnt(0)
	ds_write2_b64 v4, v[0:1], v[2:3] offset1:1
	v_mov_b32_e32 v138, 0
	v_cndmask_b32_e32 v0, v229, v231, vcc
	s_ashr_i32 s5, s4, 31
	s_mov_b32 s35, 0
	v_lshlrev_b32_e32 v135, 2, v0
	v_mov_b32_e32 v147, 0xff800000
	v_mov_b32_e32 v80, v120
	v_mov_b32_e32 v104, v146
	v_mov_b32_e32 v136, v145
	v_mov_b32_e32 v16, 0
	v_mov_b32_e32 v17, v138
	v_mov_b32_e32 v18, v138
	v_mov_b32_e32 v19, v138
	v_mov_b32_e32 v20, v138
	v_mov_b32_e32 v21, v138
	v_mov_b32_e32 v22, v138
	v_mov_b32_e32 v23, v138
	v_mov_b32_e32 v24, v138
	v_mov_b32_e32 v25, v138
	v_mov_b32_e32 v26, v138
	v_mov_b32_e32 v27, v138
	v_mov_b32_e32 v28, v138
	v_mov_b32_e32 v29, v138
	v_mov_b32_e32 v30, v138
	v_mov_b32_e32 v31, v138
	v_mov_b32_e32 v0, 0
	v_mov_b32_e32 v1, v138
	v_mov_b32_e32 v2, v138
	v_mov_b32_e32 v3, v138
	v_mov_b32_e32 v4, v138
	v_mov_b32_e32 v5, v138
	v_mov_b32_e32 v6, v138
	v_mov_b32_e32 v7, v138
	v_mov_b32_e32 v8, v138
	v_mov_b32_e32 v9, v138
	v_mov_b32_e32 v10, v138
	v_mov_b32_e32 v11, v138
	v_mov_b32_e32 v12, v138
	v_mov_b32_e32 v13, v138
	v_mov_b32_e32 v14, v138
	v_mov_b32_e32 v15, v138
	s_waitcnt lgkmcnt(0)
	s_barrier
	v_readfirstlane_b32 s85, v204
	s_mov_b32 s76, 1
	s_movk_i32 s77, 0x3400
	s_movk_i32 s78, 0x2200
	s_movk_i32 s79, 0x4400
	s_mov_b32 s80, 0
	s_movk_i32 s81, 0x3400
	s_movk_i32 s82, 0x6800
	s_mov_b32 s83, 0x8a00
	s_mov_b32 s84, 0xac00
	s_lshr_b32 s85, s85, 8
	s_mov_b32 s35, 0
	s_mov_b32 s87, 0x44800000
	v_mov_b32_e32 v105, v81
	v_mov_b32_e32 v137, v81
	v_lshl_add_u64 v[240:241], v[80:81], 1, s[6:7]
	global_load_dwordx4 v[98:101], v[240:241], off
	v_lshl_add_u64 v[240:241], v[104:105], 1, v[102:103]
	global_load_dwordx4 v[94:97], v[240:241], off
	s_cmp_eq_u32 s85, 0
	s_cbranch_scc0 .Lat_ld1
	v_lshl_add_u64 v[240:241], v[136:137], 1, s[8:9]
	global_load_dwordx4 v[90:93], v[240:241], off

.Lat_nost2:
	s_nop 7
	s_nop 3
	v_max3_f32 v128, v48, v49, v50
	v_max3_f32 v128, v128, v51, v52
	v_max3_f32 v128, v128, v53, v54
	v_max3_f32 v128, v128, v55, v56
	v_max3_f32 v128, v128, v57, v58
	v_max3_f32 v128, v128, v59, v60
	v_max3_f32 v128, v128, v61, v62
	v_max3_f32 v128, v128, v63, v32
	v_max3_f32 v128, v128, v33, v34
	v_max3_f32 v128, v128, v35, v36
	v_max3_f32 v128, v128, v37, v38
	v_max3_f32 v128, v128, v39, v40
	v_max3_f32 v128, v128, v41, v42
	v_max3_f32 v128, v128, v43, v44
	v_max3_f32 v128, v128, v45, v46
	v_max_f32_e32 v128, v128, v47
	v_mov_b32_e32 v129, v128
	s_nop 1
	v_permlane32_swap_b32_e32 v128, v129
	v_max_f32_e32 v128, v128, v129
	v_sub_f32_e32 v168, 0, v128
	v_sub_f32_e32 v169, 0, v128
	v_sub_f32_e32 v170, 0, v128
	v_sub_f32_e32 v171, 0, v128
	v_sub_f32_e32 v172, 0, v128
	v_sub_f32_e32 v173, 0, v128
	v_sub_f32_e32 v174, 0, v128
	v_sub_f32_e32 v175, 0, v128
	v_sub_f32_e32 v176, 0, v128
	v_sub_f32_e32 v177, 0, v128
	v_sub_f32_e32 v178, 0, v128
	v_sub_f32_e32 v179, 0, v128
	v_sub_f32_e32 v180, 0, v128
	v_sub_f32_e32 v181, 0, v128
	v_sub_f32_e32 v182, 0, v128
	v_sub_f32_e32 v183, 0, v128
	v_sub_f32_e32 v48, v48, v128
	v_sub_f32_e32 v49, v49, v128
	v_sub_f32_e32 v50, v50, v128
	v_sub_f32_e32 v51, v51, v128
	v_sub_f32_e32 v52, v52, v128
	v_sub_f32_e32 v53, v53, v128
	v_sub_f32_e32 v54, v54, v128
	v_sub_f32_e32 v55, v55, v128
	v_sub_f32_e32 v56, v56, v128
	v_sub_f32_e32 v57, v57, v128
	v_sub_f32_e32 v58, v58, v128
	v_sub_f32_e32 v59, v59, v128
	v_sub_f32_e32 v60, v60, v128
	v_sub_f32_e32 v61, v61, v128
	v_sub_f32_e32 v62, v62, v128
	v_sub_f32_e32 v63, v63, v128
	v_sub_f32_e32 v32, v32, v128
	v_sub_f32_e32 v33, v33, v128
	v_sub_f32_e32 v34, v34, v128
	v_sub_f32_e32 v35, v35, v128
	v_sub_f32_e32 v36, v36, v128
	v_sub_f32_e32 v37, v37, v128
	v_sub_f32_e32 v38, v38, v128
	v_sub_f32_e32 v39, v39, v128
	v_sub_f32_e32 v40, v40, v128
	v_sub_f32_e32 v41, v41, v128
	v_sub_f32_e32 v42, v42, v128
	v_sub_f32_e32 v43, v43, v128
	v_sub_f32_e32 v44, v44, v128
	v_sub_f32_e32 v45, v45, v128
	v_sub_f32_e32 v46, v46, v128
	v_sub_f32_e32 v47, v47, v128
	v_exp_f32_e32 v48, v48
	v_exp_f32_e32 v49, v49
	v_exp_f32_e32 v50, v50
	v_exp_f32_e32 v51, v51
	v_exp_f32_e32 v52, v52
	v_exp_f32_e32 v53, v53
	v_exp_f32_e32 v54, v54
	v_exp_f32_e32 v55, v55
	v_exp_f32_e32 v56, v56
	v_exp_f32_e32 v57, v57
	v_exp_f32_e32 v58, v58
	v_exp_f32_e32 v59, v59
	v_exp_f32_e32 v60, v60
	v_exp_f32_e32 v61, v61
	v_exp_f32_e32 v62, v62
	v_exp_f32_e32 v63, v63
	v_cvt_pk_bf16_f32 v148, v48, v49
	v_cvt_pk_bf16_f32 v149, v50, v51
	v_cvt_pk_bf16_f32 v150, v52, v53
	v_cvt_pk_bf16_f32 v151, v54, v55
	v_cvt_pk_bf16_f32 v152, v56, v57
	v_cvt_pk_bf16_f32 v153, v58, v59
	v_cvt_pk_bf16_f32 v154, v60, v61
	v_cvt_pk_bf16_f32 v155, v62, v63
	v_add_u32_e32 v129, s82, v143
	v_add_u32_e32 v131, 0x1000, v129
	ds_read2_b64 v[184:187], v129 offset1:2
	ds_read2_b64 v[188:191], v131 offset0:32 offset1:34
	ds_read2_b64 v[192:195], v129 offset0:4 offset1:6
	ds_read2_b64 v[200:203], v131 offset0:36 offset1:38
	s_mov_b32 s86, s82
	s_mov_b32 s82, s83
	s_mov_b32 s83, s84
	s_mov_b32 s84, s86
	s_waitcnt lgkmcnt(4)
	s_barrier
.Lat_loop:
	v_add_u32_e32 v130, s81, v142
	ds_read_b128 v[206:209], v130
	ds_read_b128 v[210:213], v130 offset:32
	s_waitcnt lgkmcnt(5)
	v_mfma_f32_32x32x16_bf16 v[16:31], v[184:187], v[148:151], v[16:31]
	ds_read2_b64 v[184:187], v129 offset0:8 offset1:10
	v_add_f32_e32 v226, v48, v49
	v_add_f32_e32 v227, v56, v57
	v_add_f32_e32 v226, v226, v50
	ds_read_b128 v[214:217], v130 offset:64
	ds_read_b128 v[218:221], v130 offset:96
	s_waitcnt lgkmcnt(7)
	v_mfma_f32_32x32x16_bf16 v[0:15], v[188:191], v[148:151], v[0:15]
	ds_read2_b64 v[188:191], v131 offset0:40 offset1:42
	v_add_f32_e32 v227, v227, v58
	v_add_f32_e32 v226, v226, v51
	v_add_f32_e32 v227, v227, v59
	v_add_f32_e32 v226, v226, v52
	ds_read_b128 v[222:225], v130 offset:128
	ds_read_b128 v[164:167], v130 offset:160
	s_waitcnt lgkmcnt(9)
	v_mfma_f32_32x32x16_bf16 v[16:31], v[192:195], v[152:155], v[16:31]
	ds_read2_b64 v[192:195], v129 offset0:12 offset1:14
	v_add_f32_e32 v227, v227, v60
	v_add_f32_e32 v226, v226, v53
	v_add_f32_e32 v227, v227, v61
	s_waitcnt lgkmcnt(9)
	v_mfma_f32_32x32x16_bf16 v[0:15], v[200:203], v[152:155], v[0:15]
	ds_read2_b64 v[200:203], v131 offset0:44 offset1:46
	v_add_f32_e32 v226, v226, v54
	v_add_f32_e32 v227, v227, v62
	v_add_f32_e32 v226, v226, v55
	v_add_f32_e32 v227, v227, v63
	s_waitcnt lgkmcnt(2)
	v_mfma_f32_32x32x16_bf16 v[48:63], v[206:209], v[86:89], v[168:183]
	ds_read_b128 v[206:209], v130 offset:6656
	v_exp_f32_e32 v32, v32
	v_exp_f32_e32 v33, v33
	v_mfma_f32_32x32x16_bf16 v[48:63], v[210:213], v[82:85], v[48:63]
	ds_read_b128 v[210:213], v130 offset:6688
	v_exp_f32_e32 v34, v34
	v_exp_f32_e32 v35, v35
	v_exp_f32_e32 v36, v36
	v_mfma_f32_32x32x16_bf16 v[48:63], v[214:217], v[76:79], v[48:63]
	ds_read_b128 v[214:217], v130 offset:6720
	v_exp_f32_e32 v37, v37
	v_exp_f32_e32 v38, v38
	v_exp_f32_e32 v39, v39
	v_mfma_f32_32x32x16_bf16 v[48:63], v[218:221], v[72:75], v[48:63]
	ds_read_b128 v[218:221], v130 offset:6752
	v_exp_f32_e32 v40, v40
	v_exp_f32_e32 v41, v41
	v_mfma_f32_32x32x16_bf16 v[48:63], v[222:225], v[68:71], v[48:63]
	ds_read_b128 v[222:225], v130 offset:6784
	v_exp_f32_e32 v42, v42
	v_exp_f32_e32 v43, v43
	v_exp_f32_e32 v44, v44
	v_mfma_f32_32x32x16_bf16 v[48:63], v[164:167], v[64:67], v[48:63]
	ds_read_b128 v[164:167], v130 offset:6816
	v_exp_f32_e32 v45, v45
	v_exp_f32_e32 v46, v46
	v_exp_f32_e32 v47, v47
	v_cvt_pk_bf16_f32 v156, v32, v33
	v_cvt_pk_bf16_f32 v157, v34, v35
	v_cvt_pk_bf16_f32 v158, v36, v37
	v_cvt_pk_bf16_f32 v159, v38, v39
	v_cvt_pk_bf16_f32 v160, v40, v41
	v_cvt_pk_bf16_f32 v161, v42, v43
	v_cvt_pk_bf16_f32 v162, v44, v45
	v_cvt_pk_bf16_f32 v163, v46, v47
	v_mfma_f32_32x32x16_bf16 v[16:31], v[184:187], v[156:159], v[16:31]
	v_add_f32_e32 v248, v32, v33
	v_add_f32_e32 v249, v40, v41
	v_add_f32_e32 v248, v248, v34
	v_add_f32_e32 v249, v249, v42
	v_add_f32_e32 v248, v248, v35
	v_mfma_f32_32x32x16_bf16 v[0:15], v[188:191], v[156:159], v[0:15]
	v_add_f32_e32 v249, v249, v43
	v_add_f32_e32 v248, v248, v36
	v_add_f32_e32 v249, v249, v44
	v_add_f32_e32 v248, v248, v37
	v_add_f32_e32 v249, v249, v45
	s_waitcnt lgkmcnt(7)
	v_mfma_f32_32x32x16_bf16 v[16:31], v[192:195], v[160:163], v[16:31]
	v_add_f32_e32 v248, v248, v38
	v_add_f32_e32 v249, v249, v46
	v_add_f32_e32 v248, v248, v39
	v_add_f32_e32 v249, v249, v47
	v_add_f32_e32 v226, v226, v227
	s_waitcnt lgkmcnt(6)
	v_mfma_f32_32x32x16_bf16 v[0:15], v[200:203], v[160:163], v[0:15]
	v_add_f32_e32 v248, v248, v249
	v_add_f32_e32 v226, v226, v248
	v_cmp_lt_f32_e32 vcc, s87, v226
	s_mov_b64 s[88:89], vcc
	v_add_f32_e32 v138, v138, v226
	s_waitcnt lgkmcnt(0)
	v_mfma_f32_32x32x16_bf16 v[32:47], v[206:209], v[86:89], v[168:183]
	v_exp_f32_e32 v48, v48
	v_exp_f32_e32 v49, v49
	v_exp_f32_e32 v50, v50
	v_mfma_f32_32x32x16_bf16 v[32:47], v[210:213], v[82:85], v[32:47]
	v_exp_f32_e32 v51, v51
	v_exp_f32_e32 v52, v52
	v_exp_f32_e32 v53, v53
	v_mfma_f32_32x32x16_bf16 v[32:47], v[214:217], v[76:79], v[32:47]
	v_exp_f32_e32 v54, v54
	v_exp_f32_e32 v55, v55
	v_exp_f32_e32 v56, v56
	v_mfma_f32_32x32x16_bf16 v[32:47], v[218:221], v[72:75], v[32:47]
	v_exp_f32_e32 v57, v57
	v_exp_f32_e32 v58, v58
	v_exp_f32_e32 v59, v59
	v_mfma_f32_32x32x16_bf16 v[32:47], v[222:225], v[68:71], v[32:47]
	v_exp_f32_e32 v60, v60
	v_exp_f32_e32 v61, v61
	v_exp_f32_e32 v62, v62
	v_mfma_f32_32x32x16_bf16 v[32:47], v[164:167], v[64:67], v[32:47]
	v_exp_f32_e32 v63, v63
	v_cvt_pk_bf16_f32 v148, v48, v49
	v_cvt_pk_bf16_f32 v149, v50, v51
	v_cvt_pk_bf16_f32 v150, v52, v53
	v_cvt_pk_bf16_f32 v151, v54, v55
	v_cvt_pk_bf16_f32 v152, v56, v57
	v_cvt_pk_bf16_f32 v153, v58, v59
	v_cvt_pk_bf16_f32 v154, v60, v61
	v_cvt_pk_bf16_f32 v155, v62, v63
	s_cmpk_gt_u32 s76, 0x47
	s_cbranch_scc1 .Lat_nost6
	s_waitcnt vmcnt(0)
	v_add_u32_e32 v242, s77, v109
	ds_write_b128 v242, v[98:101]
	s_cmp_eq_u32 s85, 0
	s_cbranch_scc0 .Lat_stB7
	v_add_u32_e32 v242, s77, v140
	ds_write_b128 v242, v[94:97]
	v_add_u32_e32 v242, s78, v141
	ds_write2_b64 v242, v[90:91], v[92:93] offset1:1
	s_branch .Lat_std8

.Lat_resc:
	s_nop 7
	s_nop 7
	v_mov_b32_e32 v242, v226
	v_mov_b32_e32 v243, v226
	s_nop 1
	v_permlane32_swap_b32_e32 v242, v243
	v_max_f32_e32 v242, v242, v243
	v_log_f32_e32 v242, v242
	s_nop 0
	v_max_f32_e32 v242, 0, v242
	v_exp_f32_e64 v243, -v242
	v_sub_f32_e32 v32, v32, v242
	v_sub_f32_e32 v33, v33, v242
	v_sub_f32_e32 v34, v34, v242
	v_sub_f32_e32 v35, v35, v242
	v_sub_f32_e32 v36, v36, v242
	v_sub_f32_e32 v37, v37, v242
	v_sub_f32_e32 v38, v38, v242
	v_sub_f32_e32 v39, v39, v242
	v_sub_f32_e32 v40, v40, v242
	v_sub_f32_e32 v41, v41, v242
	v_sub_f32_e32 v42, v42, v242
	v_sub_f32_e32 v43, v43, v242
	v_sub_f32_e32 v44, v44, v242
	v_sub_f32_e32 v45, v45, v242
	v_sub_f32_e32 v46, v46, v242
	v_sub_f32_e32 v47, v47, v242
	v_sub_f32_e32 v168, v168, v242
	v_sub_f32_e32 v169, v169, v242
	v_sub_f32_e32 v170, v170, v242
	v_sub_f32_e32 v171, v171, v242
	v_sub_f32_e32 v172, v172, v242
	v_sub_f32_e32 v173, v173, v242
	v_sub_f32_e32 v174, v174, v242
	v_sub_f32_e32 v175, v175, v242
	v_sub_f32_e32 v176, v176, v242
	v_sub_f32_e32 v177, v177, v242
	v_sub_f32_e32 v178, v178, v242
	v_sub_f32_e32 v179, v179, v242
	v_sub_f32_e32 v180, v180, v242
	v_sub_f32_e32 v181, v181, v242
	v_sub_f32_e32 v182, v182, v242
	v_sub_f32_e32 v183, v183, v242
	v_mul_f32_e32 v48, v48, v243
	v_mul_f32_e32 v49, v49, v243
	v_mul_f32_e32 v50, v50, v243
	v_mul_f32_e32 v51, v51, v243
	v_mul_f32_e32 v52, v52, v243
	v_mul_f32_e32 v53, v53, v243
	v_mul_f32_e32 v54, v54, v243
	v_mul_f32_e32 v55, v55, v243
	v_mul_f32_e32 v56, v56, v243
	v_mul_f32_e32 v57, v57, v243
	v_mul_f32_e32 v58, v58, v243
	v_mul_f32_e32 v59, v59, v243
	v_mul_f32_e32 v60, v60, v243
	v_mul_f32_e32 v61, v61, v243
	v_mul_f32_e32 v62, v62, v243
	v_mul_f32_e32 v63, v63, v243
	v_mul_f32_e32 v0, v0, v243
	v_mul_f32_e32 v1, v1, v243
	v_mul_f32_e32 v2, v2, v243
	v_mul_f32_e32 v3, v3, v243
	v_mul_f32_e32 v4, v4, v243
	v_mul_f32_e32 v5, v5, v243
	v_mul_f32_e32 v6, v6, v243
	v_mul_f32_e32 v7, v7, v243
	v_mul_f32_e32 v8, v8, v243
	v_mul_f32_e32 v9, v9, v243
	v_mul_f32_e32 v10, v10, v243
	v_mul_f32_e32 v11, v11, v243
	v_mul_f32_e32 v12, v12, v243
	v_mul_f32_e32 v13, v13, v243
	v_mul_f32_e32 v14, v14, v243
	v_mul_f32_e32 v15, v15, v243
	v_mul_f32_e32 v16, v16, v243
	v_mul_f32_e32 v17, v17, v243
	v_mul_f32_e32 v18, v18, v243
	v_mul_f32_e32 v19, v19, v243
	v_mul_f32_e32 v20, v20, v243
	v_mul_f32_e32 v21, v21, v243
	v_mul_f32_e32 v22, v22, v243
	v_mul_f32_e32 v23, v23, v243
	v_mul_f32_e32 v24, v24, v243
	v_mul_f32_e32 v25, v25, v243
	v_mul_f32_e32 v26, v26, v243
	v_mul_f32_e32 v27, v27, v243
	v_mul_f32_e32 v28, v28, v243
	v_mul_f32_e32 v29, v29, v243
	v_mul_f32_e32 v30, v30, v243
	v_mul_f32_e32 v31, v31, v243
	v_mul_f32_e32 v138, v138, v243
	v_cvt_pk_bf16_f32 v148, v48, v49
	v_cvt_pk_bf16_f32 v149, v50, v51
	v_cvt_pk_bf16_f32 v150, v52, v53
	v_cvt_pk_bf16_f32 v151, v54, v55
	v_cvt_pk_bf16_f32 v152, v56, v57
	v_cvt_pk_bf16_f32 v153, v58, v59
	v_cvt_pk_bf16_f32 v154, v60, v61
	v_cvt_pk_bf16_f32 v155, v62, v63
	s_branch .Lat_resc_back
